# scan: critical waves 0-3 at s_setprio 3 instead of 2 (same double-buffered barrier-free step)
# speedup vs baseline: 1.0035x; 1.0035x over previous
.LBB0_1144:
	s_ashr_i32 s5, s85, 2
	s_lshl_b32 s7, s85, 6
	s_lshl_b32 s6, s5, 8
	s_and_b32 s10, s7, 0x80
	s_or_b32 s6, s6, s10
	s_and_b32 s4, s85, 1
	s_bfe_i32 s8, s85, 0x10000
	s_ashr_i32 s12, s85, 4
	s_mul_hi_i32 s7, s6, 0x4200
	s_mulk_i32 s6, 0x4200
	s_and_b32 s11, s5, 3
	s_add_u32 s6, s56, s6
	s_addc_u32 s7, s57, s7
	s_cmp_eq_u32 s4, 0
	s_cselect_b64 s[4:5], -1, 0
	v_mov_b32_e32 v3, v148
	s_and_b64 s[14:15], s[4:5], exec
	s_mov_b32 s9, 0xc400000
	s_barrier
	s_cselect_b32 s9, s9, 0x10600000
	v_ashrrev_i32_e32 v14, 6, v3
	s_mov_b32 s13, 0x14800000
	v_add_u32_e32 v0, -4, v14
	s_cselect_b32 s13, s13, 0x1c800000
	s_cselect_b32 s86, 63, 0
	s_add_u32 s70, s54, s9
	v_lshrrev_b32_e32 v15, 1, v0
	v_and_b32_e32 v16, 1, v14
	s_addc_u32 s71, s55, 0
	v_cmp_gt_u32_e32 vcc, v16, v15
	s_add_u32 s13, s54, s13
	s_addc_u32 s14, s55, 0
	v_cndmask_b32_e64 v0, 0, 1, vcc
	v_cmp_lt_u32_e32 vcc, v16, v15
	s_lshl_b32 s87, s12, 8
	s_and_b32 s8, s8, 0xc0
	v_cndmask_b32_e64 v4, 0, 1, vcc
	s_add_i32 s87, s87, 0x10000
	v_cndmask_b32_e64 v17, v4, v0, s[4:5]
	s_or_b32 s15, s87, s8
	v_lshlrev_b32_e32 v4, 2, v3
	s_lshl_b32 s16, s8, 1
	s_or_b32 s8, s15, s86
	v_ashrrev_i32_e32 v149, 4, v3
	v_lshlrev_b32_e32 v0, 3, v3
	v_and_b32_e32 v21, 4, v4
	s_ashr_i32 s9, s8, 31
	v_and_b32_e32 v22, 0x78, v0
	v_add_u32_e32 v4, s15, v149
	v_ashrrev_i32_e32 v5, 31, v4
	v_lshl_or_b32 v136, s11, 7, v22
	s_lshl_b64 s[8:9], s[8:9], 10
	v_lshlrev_b64 v[4:5], 10, v[4:5]
	s_waitcnt vmcnt(11)
	v_lshlrev_b32_e32 v8, 1, v136
	s_add_u32 s8, s70, s8
	v_or_b32_e32 v4, v4, v8
	s_addc_u32 s9, s71, s9
	s_lshl_b32 s17, s11, 8
	v_add_u32_e32 v23, 0x200, v3
	s_waitcnt vmcnt(5)
	v_lshl_add_u64 v[6:7], s[76:77], 0, v[4:5]
	s_add_u32 s8, s8, s17
	v_ashrrev_i32_e32 v172, 4, v23
	s_addc_u32 s9, s9, 0
	v_lshlrev_b32_e32 v0, 1, v22
	global_load_dwordx4 v[138:141], v[6:7], off
	global_load_dwordx4 v[142:145], v0, s[8:9]
	v_add_u32_e32 v6, s15, v172
	v_ashrrev_i32_e32 v7, 31, v6
	v_lshlrev_b64 v[6:7], 10, v[6:7]
	v_lshl_add_u64 v[4:5], s[70:71], 0, v[4:5]
	v_or_b32_e32 v6, v6, v8
	v_lshl_add_u64 v[8:9], s[76:77], 0, v[6:7]
	global_load_dwordx4 v[156:159], v[4:5], off
	global_load_dwordx4 v[160:163], v[8:9], off
	v_lshl_add_u64 v[4:5], s[70:71], 0, v[6:7]
	global_load_dwordx4 v[164:167], v[4:5], off
	v_ashrrev_i32_e32 v12, 3, v3
	v_mov_b64_e32 v[4:5], s[6:7]
	v_mad_i64_i32 v[6:7], s[6:7], v12, s33, v[4:5]
	v_add_u32_e32 v12, 64, v12
	s_or_b32 s48, s16, 0x4000
	v_lshlrev_b32_e32 v24, 4, v3
	v_mad_i64_i32 v[4:5], s[6:7], v12, s33, v[4:5]
	v_lshl_add_u64 v[8:9], v[6:7], 0, s[48:49]
	v_and_b32_e32 v10, 0x70, v24
	v_mov_b32_e32 v11, v1
	v_lshl_add_u64 v[12:13], v[4:5], 0, s[48:49]
	v_lshl_add_u64 v[8:9], v[8:9], 0, v[10:11]
	v_lshl_add_u64 v[12:13], v[12:13], 0, v[10:11]
	global_load_dwordx4 v[128:131], v[8:9], off
	global_load_dwordx4 v[132:135], v[12:13], off
	v_ashrrev_i32_e32 v8, 7, v3
	v_lshlrev_b32_e32 v9, 1, v149
	v_lshrrev_b32_e32 v12, 1, v21
	v_and_b32_e32 v25, 14, v9
	v_lshlrev_b32_e32 v9, 7, v22
	v_xor_b32_e32 v13, v12, v8
	v_lshl_add_u32 v26, v13, 4, v9
	v_or_b32_e32 v13, 2, v22
	v_or_b32_e32 v29, 3, v22
	v_or_b32_e32 v32, 8, v22
	v_or_b32_e32 v35, 9, v22
	v_or_b32_e32 v38, 10, v22
	v_or_b32_e32 v22, 11, v22
	v_lshlrev_b32_e32 v27, 7, v13
	v_lshrrev_b32_e32 v13, 1, v13
	v_lshlrev_b32_e32 v30, 7, v29
	v_lshrrev_b32_e32 v29, 1, v29
	v_lshlrev_b32_e32 v33, 7, v32
	v_lshrrev_b32_e32 v32, 1, v32
	v_lshlrev_b32_e32 v36, 7, v35
	v_lshrrev_b32_e32 v35, 1, v35
	v_lshlrev_b32_e32 v39, 7, v38
	v_lshrrev_b32_e32 v38, 1, v38
	v_lshlrev_b32_e32 v41, 7, v22
	v_lshrrev_b32_e32 v22, 1, v22
	v_bitop3_b32 v28, v13, v8, 3 bitop3:0x6c
	v_bitop3_b32 v31, v29, v8, 3 bitop3:0x6c
	v_bitop3_b32 v34, v32, v8, 6 bitop3:0x6c
	v_bitop3_b32 v37, v35, v8, 6 bitop3:0x6c
	v_bitop3_b32 v40, v38, v8, 7 bitop3:0x6c
	v_bitop3_b32 v8, v22, v8, 7 bitop3:0x6c
	v_xor_b32_e32 v43, v149, v3
	v_lshl_add_u32 v42, v8, 4, v41
	v_lshlrev_b32_e32 v8, 8, v149
	v_lshlrev_b32_e32 v43, 4, v43
	s_add_u32 s8, s70, s17
	v_and_or_b32 v173, v43, s84, v8
	v_ashrrev_i32_e32 v8, 7, v23
	s_addc_u32 s9, s71, 0
	v_lshl_add_u64 v[154:155], v[4:5], 0, v[10:11]
	s_lshl_b32 s88, s12, 13
	v_lshlrev_b32_e32 v4, 5, v3
	v_lshlrev_b32_e32 v5, 2, v21
	s_movk_i32 s12, 0xffc0
	v_xor_b32_e32 v12, v12, v8
	s_nop 0
	v_lshl_add_u32 v43, v12, 4, v9
	v_bitop3_b32 v9, v13, v8, 3 bitop3:0x6c
	v_add_u32_e32 v176, 0x16000, v4
	v_and_b32_e32 v4, 1, v17
	v_lshl_add_u32 v28, v28, 4, v27
	v_lshl_add_u32 v27, v9, 4, v27
	v_bitop3_b32 v9, v29, v8, 3 bitop3:0x6c
	v_cmp_eq_u32_e32 vcc, 1, v4
	v_lshl_add_u32 v29, v9, 4, v30
	v_bitop3_b32 v9, v32, v8, 6 bitop3:0x6c
	s_xor_b64 s[78:79], vcc, -1
	s_lshl_b32 s11, s11, 9
	v_lshl_add_u32 v31, v31, 4, v30
	v_lshl_add_u32 v30, v9, 4, v33
	v_bitop3_b32 v9, v35, v8, 6 bitop3:0x6c
	s_add_u32 s11, s13, s11
	v_and_b32_e32 v18, 31, v3
	v_lshl_add_u32 v32, v9, 4, v36
	v_bitop3_b32 v9, v38, v8, 7 bitop3:0x6c
	v_lshl_add_u64 v[146:147], s[8:9], 0, v[0:1]
	v_lshlrev_b32_e32 v0, 5, v14
	s_addc_u32 s12, s14, 0
	s_lshl_b32 s10, s10, 1
	v_lshrrev_b32_e32 v2, 5, v3
	v_bfe_u32 v19, v3, 5, 1
	v_bfe_u32 v20, v3, 1, 3
	v_lshl_add_u32 v34, v34, 4, v33
	v_lshl_add_u32 v33, v9, 4, v39
	v_xor_b32_e32 v9, v172, v3
	v_and_b32_e32 v35, 0xffffff80, v24
	v_bitop3_b32 v24, v24, s51, v3 bitop3:0x48
	v_cmp_gt_i32_e64 s[6:7], 16, v3
	v_lshl_add_u64 v[152:153], v[6:7], 0, v[10:11]
	v_and_b32_e32 v0, 0x60, v0
	v_lshlrev_b32_e32 v177, 8, v18
	v_and_b32_e32 v6, 15, v3
	v_lshlrev_b32_e32 v3, 1, v3
	s_add_u32 s10, s11, s10
	v_lshl_or_b32 v179, v16, 13, v177
	v_lshl_or_b32 v7, v16, 5, v18
	v_and_b32_e32 v16, 14, v3
	v_or_b32_e32 v3, v0, v18
	s_addc_u32 s11, s12, 0
	v_lshlrev_b32_e32 v0, 1, v0
	v_lshl_add_u64 v[4:5], s[10:11], 0, v[0:1]
	v_lshlrev_b32_e32 v0, 1, v18
	v_lshl_add_u64 v[4:5], v[4:5], 0, v[0:1]
	v_bitop3_b32 v0, v2, v6, 1 bitop3:0x6c
	v_lshlrev_b32_e32 v184, 4, v0
	v_bitop3_b32 v0, v19, v6, 2 bitop3:0x36
	v_lshlrev_b32_e32 v185, 4, v0
	v_bitop3_b32 v0, v19, v6, 4 bitop3:0x36
	v_lshlrev_b32_e32 v186, 4, v0
	v_bitop3_b32 v0, v19, v6, 6 bitop3:0x36
	v_lshlrev_b32_e32 v187, 4, v0
	v_bitop3_b32 v0, v19, v6, 8 bitop3:0x36
	v_bitop3_b32 v8, v22, v8, 7 bitop3:0x6c
	v_lshlrev_b32_e32 v188, 4, v0
	v_bitop3_b32 v0, v19, v6, 10 bitop3:0x36
	v_lshl_add_u32 v22, v8, 4, v41
	v_lshlrev_b32_e32 v8, 8, v172
	v_lshlrev_b32_e32 v9, 4, v9
	v_lshlrev_b32_e32 v189, 4, v0
	v_bitop3_b32 v0, v19, v6, 12 bitop3:0x36
	v_and_or_b32 v174, v9, s84, v8
	v_lshlrev_b32_e32 v8, 2, v19
	v_lshlrev_b32_e32 v190, 4, v0
	v_bitop3_b32 v0, v19, v6, 14 bitop3:0x36
	v_lshlrev_b32_e32 v191, 4, v0
	v_lshl_or_b32 v0, v15, 5, v8
	v_cmp_le_u32_e32 vcc, v7, v0
	v_lshlrev_b32_e32 v180, 7, v3
	v_lshrrev_b32_e32 v9, 3, v7
	v_cndmask_b32_e64 v3, 0, 1, vcc
	v_cmp_ge_u32_e32 vcc, v7, v0
	v_lshlrev_b32_e32 v8, 4, v9
	v_lshlrev_b32_e32 v181, 7, v18
	v_cndmask_b32_e64 v6, 0, 1, vcc
	v_cndmask_b32_e64 v3, v6, v3, s[4:5]
	v_and_b32_e32 v3, 1, v3
	v_cmp_eq_u32_e64 s[10:11], 1, v3
	v_lshlrev_b32_e32 v3, 7, v0
	v_lshlrev_b32_e32 v6, 5, v19
	v_bitop3_b32 v3, v3, v8, v6 bitop3:0xf6
	v_add_u32_e32 v17, 0x14000, v3
	v_or_b32_e32 v3, 1, v0
	v_cmp_gt_u32_e32 vcc, v7, v0
	v_lshl_add_u32 v37, v37, 4, v36
	v_lshl_add_u32 v40, v40, 4, v39
	v_cndmask_b32_e64 v10, 0, 1, vcc
	v_cmp_le_u32_e32 vcc, v7, v3
	v_lshlrev_b32_e32 v3, 7, v3
	v_bitop3_b32 v3, v3, v8, v6 bitop3:0xf6
	v_cndmask_b32_e64 v11, 0, 1, vcc
	v_cndmask_b32_e64 v10, v10, v11, s[4:5]
	v_add_u32_e32 v18, 0x14000, v3
	v_or_b32_e32 v3, 2, v0
	v_and_b32_e32 v10, 1, v10
	v_cmp_le_u32_e32 vcc, v7, v3
	v_cmp_eq_u32_e64 s[12:13], 1, v10
	v_lshlrev_b32_e32 v23, 1, v172
	v_cndmask_b32_e64 v10, 0, 1, vcc
	v_cmp_ge_u32_e32 vcc, v7, v3
	v_and_b32_e32 v23, 14, v23
	v_cmp_gt_i32_e64 s[8:9], 4, v14
	v_cndmask_b32_e64 v11, 0, 1, vcc
	v_cndmask_b32_e64 v10, v11, v10, s[4:5]
	v_and_b32_e32 v10, 1, v10
	v_cmp_eq_u32_e64 s[14:15], 1, v10
	v_lshrrev_b32_e32 v10, 1, v3
	v_bitop3_b32 v10, v10, v9, 3 bitop3:0x6c
	v_lshlrev_b32_e32 v10, 4, v10
	v_lshl_or_b32 v3, v3, 7, v10
	v_add_u32_e32 v21, 0x14000, v3
	v_or_b32_e32 v3, 3, v0
	v_cmp_le_u32_e32 vcc, v7, v3
	v_lshl_or_b32 v178, v15, 13, v177
	v_mov_b32_e32 v14, v1
	v_cndmask_b32_e64 v10, 0, 1, vcc
	v_cmp_ge_u32_e32 vcc, v7, v3
	v_mov_b32_e32 v15, v1
	v_lshl_or_b32 v183, v19, 4, v137
	v_cndmask_b32_e64 v11, 0, 1, vcc
	v_cndmask_b32_e64 v10, v11, v10, s[4:5]
	v_and_b32_e32 v10, 1, v10
	v_cmp_eq_u32_e64 s[16:17], 1, v10
	v_lshrrev_b32_e32 v10, 1, v3
	v_bitop3_b32 v10, v10, v9, 3 bitop3:0x6c
	v_lshlrev_b32_e32 v10, 4, v10
	v_lshl_or_b32 v3, v3, 7, v10
	v_add_u32_e32 v36, 0x14000, v3
	v_or_b32_e32 v3, 8, v0
	v_cmp_le_u32_e32 vcc, v7, v3
	v_mov_b32_e32 v12, v1
	v_mov_b32_e32 v13, v1
	v_cndmask_b32_e64 v10, 0, 1, vcc
	v_cmp_ge_u32_e32 vcc, v7, v3
	v_add_u32_e32 v197, v26, v25
	v_add_u32_e32 v198, v28, v25
	v_cndmask_b32_e64 v11, 0, 1, vcc
	v_cndmask_b32_e64 v10, v11, v10, s[4:5]
	v_and_b32_e32 v10, 1, v10
	v_cmp_eq_u32_e64 s[18:19], 1, v10
	v_lshrrev_b32_e32 v10, 1, v3
	v_bitop3_b32 v10, v10, v9, 6 bitop3:0x6c
	v_lshlrev_b32_e32 v10, 4, v10
	v_lshl_or_b32 v3, v3, 7, v10
	v_add_u32_e32 v38, 0x14000, v3
	v_or_b32_e32 v3, 9, v0
	v_cmp_le_u32_e32 vcc, v7, v3
	v_add_u32_e32 v199, v31, v25
	v_add_u32_e32 v200, v34, v25
	v_cndmask_b32_e64 v10, 0, 1, vcc
	v_cmp_ge_u32_e32 vcc, v7, v3
	v_add_u32_e32 v201, v37, v25
	v_add_u32_e32 v202, v40, v25
	v_cndmask_b32_e64 v11, 0, 1, vcc
	v_cndmask_b32_e64 v10, v11, v10, s[4:5]
	v_and_b32_e32 v10, 1, v10
	v_cmp_eq_u32_e64 s[20:21], 1, v10
	v_lshrrev_b32_e32 v10, 1, v3
	v_bitop3_b32 v10, v10, v9, 6 bitop3:0x6c
	v_lshlrev_b32_e32 v10, 4, v10
	v_lshl_or_b32 v3, v3, 7, v10
	v_add_u32_e32 v39, 0x14000, v3
	v_or_b32_e32 v3, 10, v0
	v_cmp_le_u32_e32 vcc, v7, v3
	v_add_u32_e32 v203, v42, v25
	v_add_u32_e32 v204, v43, v23
	v_cndmask_b32_e64 v10, 0, 1, vcc
	v_cmp_ge_u32_e32 vcc, v7, v3
	v_add_u32_e32 v205, v27, v23
	v_add_u32_e32 v206, v29, v23
	v_cndmask_b32_e64 v11, 0, 1, vcc
	v_cndmask_b32_e64 v10, v11, v10, s[4:5]
	v_and_b32_e32 v10, 1, v10
	v_cmp_eq_u32_e64 s[22:23], 1, v10
	v_lshrrev_b32_e32 v10, 1, v3
	v_bitop3_b32 v10, v10, v9, 7 bitop3:0x6c
	v_lshlrev_b32_e32 v10, 4, v10
	v_lshl_or_b32 v3, v3, 7, v10
	v_add_u32_e32 v41, 0x14000, v3
	v_or_b32_e32 v3, 11, v0
	v_cmp_le_u32_e32 vcc, v7, v3
	v_add_u32_e32 v207, v30, v23
	v_add_u32_e32 v208, v32, v23
	v_cndmask_b32_e64 v10, 0, 1, vcc
	v_cmp_ge_u32_e32 vcc, v7, v3
	v_add_u32_e32 v209, v33, v23
	v_add_u32_e32 v210, v22, v23
	v_cndmask_b32_e64 v11, 0, 1, vcc
	v_cndmask_b32_e64 v10, v11, v10, s[4:5]
	v_and_b32_e32 v10, 1, v10
	v_cmp_eq_u32_e64 s[24:25], 1, v10
	v_lshrrev_b32_e32 v10, 1, v3
	v_bitop3_b32 v10, v10, v9, 7 bitop3:0x6c
	v_lshlrev_b32_e32 v10, 4, v10
	v_lshl_or_b32 v3, v3, 7, v10
	v_add_u32_e32 v44, 0x14000, v3
	v_or_b32_e32 v3, 16, v0
	v_cmp_le_u32_e32 vcc, v7, v3
	v_add_u32_e32 v211, v35, v24
	v_add_u32_e32 v212, v17, v16
	v_cndmask_b32_e64 v10, 0, 1, vcc
	v_cmp_ge_u32_e32 vcc, v7, v3
	v_lshlrev_b32_e32 v3, 7, v3
	v_bitop3_b32 v3, v3, v8, v6 bitop3:0xf6
	v_cndmask_b32_e64 v11, 0, 1, vcc
	v_cndmask_b32_e64 v10, v11, v10, s[4:5]
	v_add_u32_e32 v45, 0x14000, v3
	v_or_b32_e32 v3, 17, v0
	v_and_b32_e32 v10, 1, v10
	v_cmp_le_u32_e32 vcc, v7, v3
	v_cmp_eq_u32_e64 s[26:27], 1, v10
	v_add_u32_e32 v213, v18, v16
	v_cndmask_b32_e64 v10, 0, 1, vcc
	v_cmp_ge_u32_e32 vcc, v7, v3
	v_lshlrev_b32_e32 v3, 7, v3
	v_bitop3_b32 v3, v3, v8, v6 bitop3:0xf6
	v_add_u32_e32 v46, 0x14000, v3
	v_or_b32_e32 v3, 18, v0
	v_cndmask_b32_e64 v11, 0, 1, vcc
	v_cmp_le_u32_e32 vcc, v7, v3
	v_cndmask_b32_e64 v10, v11, v10, s[4:5]
	v_and_b32_e32 v10, 1, v10
	v_cndmask_b32_e64 v6, 0, 1, vcc
	v_cmp_ge_u32_e32 vcc, v7, v3
	v_cmp_eq_u32_e64 s[28:29], 1, v10
	v_mov_b32_e32 v10, v1
	v_cndmask_b32_e64 v8, 0, 1, vcc
	v_cndmask_b32_e64 v6, v8, v6, s[4:5]
	v_and_b32_e32 v6, 1, v6
	v_cmp_eq_u32_e64 s[30:31], 1, v6
	v_lshrrev_b32_e32 v6, 1, v3
	v_bitop3_b32 v6, v6, v9, 3 bitop3:0x6c
	v_lshlrev_b32_e32 v6, 4, v6
	v_lshl_or_b32 v3, v3, 7, v6
	v_add_u32_e32 v47, 0x14000, v3
	v_or_b32_e32 v3, 19, v0
	v_cmp_le_u32_e32 vcc, v7, v3
	v_mov_b32_e32 v11, v1
	v_add_u32_e32 v214, v21, v16
	v_cndmask_b32_e64 v6, 0, 1, vcc
	v_cmp_ge_u32_e32 vcc, v7, v3
	v_add_u32_e32 v215, v36, v16
	v_add_u32_e32 v216, v38, v16
	v_cndmask_b32_e64 v8, 0, 1, vcc
	v_cndmask_b32_e64 v6, v8, v6, s[4:5]
	v_and_b32_e32 v6, 1, v6
	v_cmp_eq_u32_e64 s[34:35], 1, v6
	v_lshrrev_b32_e32 v6, 1, v3
	v_bitop3_b32 v6, v6, v9, 3 bitop3:0x6c
	v_lshlrev_b32_e32 v6, 4, v6
	v_lshl_or_b32 v3, v3, 7, v6
	v_add_u32_e32 v48, 0x14000, v3
	v_or_b32_e32 v3, 24, v0
	v_cmp_le_u32_e32 vcc, v7, v3
	v_add_u32_e32 v217, v39, v16
	v_add_u32_e32 v218, v41, v16
	v_cndmask_b32_e64 v6, 0, 1, vcc
	v_cmp_ge_u32_e32 vcc, v7, v3
	v_add_u32_e32 v219, v44, v16
	v_add_u32_e32 v220, v45, v16
	v_cndmask_b32_e64 v8, 0, 1, vcc
	v_cndmask_b32_e64 v6, v8, v6, s[4:5]
	v_and_b32_e32 v6, 1, v6
	v_cmp_eq_u32_e64 s[36:37], 1, v6
	v_lshrrev_b32_e32 v6, 1, v3
	v_bitop3_b32 v6, v6, v9, 6 bitop3:0x6c
	v_lshlrev_b32_e32 v6, 4, v6
	v_lshl_or_b32 v3, v3, 7, v6
	v_add_u32_e32 v49, 0x14000, v3
	v_or_b32_e32 v3, 25, v0
	v_cmp_le_u32_e32 vcc, v7, v3
	v_add_u32_e32 v221, v46, v16
	v_add_u32_e32 v222, v47, v16
	v_cndmask_b32_e64 v6, 0, 1, vcc
	v_cmp_ge_u32_e32 vcc, v7, v3
	v_add_u32_e32 v223, v48, v16
	v_add_u32_e32 v224, v49, v16
	v_cndmask_b32_e64 v8, 0, 1, vcc
	v_cndmask_b32_e64 v6, v8, v6, s[4:5]
	v_and_b32_e32 v6, 1, v6
	v_cmp_eq_u32_e64 s[38:39], 1, v6
	v_lshrrev_b32_e32 v6, 1, v3
	v_bitop3_b32 v6, v6, v9, 6 bitop3:0x6c
	v_lshlrev_b32_e32 v6, 4, v6
	v_lshl_or_b32 v3, v3, 7, v6
	v_add_u32_e32 v50, 0x14000, v3
	v_or_b32_e32 v3, 26, v0
	v_cmp_le_u32_e32 vcc, v7, v3
	v_or_b32_e32 v0, 27, v0
	v_add_u32_e32 v225, v50, v16
	v_cndmask_b32_e64 v6, 0, 1, vcc
	v_cmp_ge_u32_e32 vcc, v7, v3
	v_or_b32_e32 v182, 0x14000, v181
	s_waitcnt vmcnt(16)
	v_mov_b64_e32 v[170:171], 0
	v_cndmask_b32_e64 v8, 0, 1, vcc
	v_cndmask_b32_e64 v6, v8, v6, s[4:5]
	v_and_b32_e32 v6, 1, v6
	v_cmp_eq_u32_e64 s[40:41], 1, v6
	v_lshrrev_b32_e32 v6, 1, v3
	v_bitop3_b32 v6, v6, v9, 7 bitop3:0x6c
	v_lshlrev_b32_e32 v6, 4, v6
	v_lshl_or_b32 v3, v3, 7, v6
	v_cmp_le_u32_e32 vcc, v7, v0
	v_add_u32_e32 v51, 0x14000, v3
	v_mov_b32_e32 v8, v1
	v_cndmask_b32_e64 v3, 0, 1, vcc
	v_cmp_ge_u32_e32 vcc, v7, v0
	v_mov_b32_e32 v7, v1
	v_add_u32_e32 v226, v51, v16
	v_cndmask_b32_e64 v6, 0, 1, vcc
	v_cndmask_b32_e64 v3, v6, v3, s[4:5]
	v_and_b32_e32 v3, 1, v3
	v_cmp_eq_u32_e64 s[42:43], 1, v3
	v_lshrrev_b32_e32 v3, 1, v0
	v_bitop3_b32 v3, v3, v9, 7 bitop3:0x6c
	v_lshlrev_b32_e32 v3, 4, v3
	v_lshl_or_b32 v0, v0, 7, v3
	v_add_u32_e32 v52, 0x14000, v0
	v_bitop3_b32 v0, v2, v20, 1 bitop3:0x6c
	v_lshlrev_b32_e32 v192, 4, v0
	v_bitop3_b32 v0, v19, v20, 2 bitop3:0x36
	v_lshlrev_b32_e32 v193, 4, v0
	v_bitop3_b32 v0, v19, v20, 4 bitop3:0x36
	v_lshlrev_b32_e32 v195, 4, v0
	v_bitop3_b32 v0, v19, v20, 6 bitop3:0x36
	v_lshlrev_b32_e32 v196, 4, v0
	v_lshlrev_b32_e32 v0, 13, v19
	v_lshl_add_u64 v[168:169], v[4:5], 0, v[0:1]
	v_mov_b32_e32 v0, v1
	v_mov_b32_e32 v2, v1
	v_mov_b32_e32 v3, v1
	v_mov_b32_e32 v4, v1
	v_mov_b32_e32 v5, v1
	v_mov_b32_e32 v6, v1
	v_mov_b32_e32 v9, v1
	v_add_u32_e32 v227, v52, v16
	v_mov_b64_e32 v[30:31], v[14:15]
	v_mov_b64_e32 v[46:47], v[14:15]
	v_mov_b64_e32 v[62:63], v[14:15]
	v_mov_b64_e32 v[78:79], v[14:15]
	s_movk_i32 s89, 0x82
	v_mov_b64_e32 v[28:29], v[12:13]
	v_mov_b64_e32 v[26:27], v[10:11]
	v_mov_b64_e32 v[24:25], v[8:9]
	v_mov_b64_e32 v[22:23], v[6:7]
	v_mov_b64_e32 v[20:21], v[4:5]
	v_mov_b64_e32 v[18:19], v[2:3]
	v_mov_b64_e32 v[16:17], v[0:1]
	v_mov_b64_e32 v[44:45], v[12:13]
	v_mov_b64_e32 v[42:43], v[10:11]
	v_mov_b64_e32 v[40:41], v[8:9]
	v_mov_b64_e32 v[38:39], v[6:7]
	v_mov_b64_e32 v[36:37], v[4:5]
	v_mov_b64_e32 v[34:35], v[2:3]
	v_mov_b64_e32 v[32:33], v[0:1]
	v_mov_b64_e32 v[60:61], v[12:13]
	v_mov_b64_e32 v[58:59], v[10:11]
	v_mov_b64_e32 v[56:57], v[8:9]
	v_mov_b64_e32 v[54:55], v[6:7]
	v_mov_b64_e32 v[52:53], v[4:5]
	v_mov_b64_e32 v[50:51], v[2:3]
	v_mov_b64_e32 v[48:49], v[0:1]
	v_mov_b64_e32 v[76:77], v[12:13]
	v_mov_b64_e32 v[74:75], v[10:11]
	v_mov_b64_e32 v[72:73], v[8:9]
	v_mov_b64_e32 v[70:71], v[6:7]
	v_mov_b64_e32 v[68:69], v[4:5]
	v_mov_b64_e32 v[66:67], v[2:3]
	v_mov_b64_e32 v[64:65], v[0:1]
	s_mov_b32 s81, s49
	v_mov_b64_e32 v[6:7], 0
	v_mov_b64_e32 v[8:9], 0
	v_mov_b64_e32 v[10:11], 0
	v_and_b32_e32 v113, 15, v148
	v_bfe_u32 v114, v148, 5, 1
	v_lshlrev_b32_e32 v115, 2, v113
	v_and_b32_e32 v115, 12, v115
	v_lshrrev_b32_e32 v116, 2, v113
	v_or_b32_e32 v115, v115, v116
	v_xor_b32_e32 v115, v115, v114
	v_xor_b32_e32 v116, 0, v115
	v_lshlrev_b32_e32 v184, 4, v116
	v_xor_b32_e32 v116, 2, v115
	v_lshlrev_b32_e32 v185, 4, v116
	v_xor_b32_e32 v116, 4, v115
	v_lshlrev_b32_e32 v186, 4, v116
	v_xor_b32_e32 v116, 6, v115
	v_lshlrev_b32_e32 v187, 4, v116
	v_xor_b32_e32 v116, 8, v115
	v_lshlrev_b32_e32 v188, 4, v116
	v_xor_b32_e32 v116, 10, v115
	v_lshlrev_b32_e32 v189, 4, v116
	v_xor_b32_e32 v116, 12, v115
	v_lshlrev_b32_e32 v190, 4, v116
	v_xor_b32_e32 v116, 14, v115
	v_lshlrev_b32_e32 v191, 4, v116
	v_lshlrev_b32_e32 v116, 2, v149
	v_and_b32_e32 v116, 12, v116
	v_bfe_u32 v117, v149, 2, 2
	v_or_b32_e32 v116, v116, v117
	v_and_b32_e32 v117, 14, v113
	v_xor_b32_e32 v116, v116, v117
	v_lshlrev_b32_e32 v116, 4, v116
	v_lshl_or_b32 v173, v149, 8, v116
	v_and_b32_e32 v117, 1, v113
	v_lshl_or_b32 v173, v117, 3, v173
	v_xor_b32_e32 v174, 16, v173
	v_mov_b64_e32 v[232:233], 0
	v_mov_b64_e32 v[234:235], 0
	v_and_b32_e32 v116, 3, v148
	v_bfe_u32 v117, v148, 2, 2
	v_bfe_u32 v118, v148, 4, 1
	v_and_b32_e32 v119, 1, v116
	v_lshl_or_b32 v119, v118, 1, v119
	v_lshlrev_b32_e32 v120, 1, v114
	v_xor_b32_e32 v119, v119, v120
	v_lshl_or_b32 v119, v117, 2, v119
	v_lshlrev_b32_e32 v119, 4, v119
	v_lshrrev_b32_e32 v120, 1, v116
	v_lshl_or_b32 v119, v120, 3, v119
	v_lshl_add_u32 v120, v114, 3, v117
	v_lshl_or_b32 v119, v120, 8, v119
	v_add_u32_e32 v197, 0x4000, v119
	v_xor_b32_e32 v198, 64, v197
	v_xor_b32_e32 v199, 0x80, v197
	v_xor_b32_e32 v200, 0xc0, v197
	v_xor_b32_e32 v201, 16, v197
	v_xor_b32_e32 v202, 16, v198
	v_xor_b32_e32 v203, 16, v199
	v_xor_b32_e32 v204, 16, v200
	v_add_u32_e32 v182, 0x4000, v182
	v_add_u32_e32 v176, 0x4000, v176
	v_add_u32_e32 v183, 0x4000, v183
	v_add_u32_e32 v212, 0x4000, v212
	v_add_u32_e32 v213, 0x4000, v213
	v_add_u32_e32 v214, 0x4000, v214
	v_add_u32_e32 v215, 0x4000, v215
	v_add_u32_e32 v216, 0x4000, v216
	v_add_u32_e32 v217, 0x4000, v217
	v_add_u32_e32 v218, 0x4000, v218
	v_add_u32_e32 v219, 0x4000, v219
	v_add_u32_e32 v220, 0x4000, v220
	v_add_u32_e32 v221, 0x4000, v221
	v_add_u32_e32 v222, 0x4000, v222
	v_add_u32_e32 v223, 0x4000, v223
	v_add_u32_e32 v224, 0x4000, v224
	v_add_u32_e32 v225, 0x4000, v225
	v_add_u32_e32 v226, 0x4000, v226
	v_add_u32_e32 v227, 0x4000, v227
	s_cmp_lg_u64 s[8:9], 0
	s_cbranch_scc0 .Lscan_noprio
	s_setprio 3
